# P3 bias reduction hidden behind the epilogue (38 WGs no longer start their GEMM late)
# speedup vs baseline: 1.0032x; 1.0032x over previous
; __global__ void __launch_bounds__(512, 2) hybrid_fwd(Args args) {
;     ...
;     if (IN(3)) {
;         for (int idx = blk * 512 + tid; idx < 2 * NBIAS; idx += G * 512) { const int bb = idx / NBIAS, col = idx - bb * NBIAS; float sacc = 0.f;
; #pragma unroll
;             for (int kb = 0; kb < 16; ++kb) sacc += BIASP[((size_t)bb * 16 + kb) * NBIAS + col];
;             BIAS[idx] = sacc; }
;         pg8::Gemm g{ACT, W2, M, DM, DFF}; pg8::StaticOrder S; S.init(M, DM, G, blk); pg8::EpiRes2<false, true> E{x, XB1, mod + 2 * DM, 0.5f, ROWP2};
.LBB0_262:
	s_cmp_lt_i32 s82, 4
	s_cselect_b64 s[4:5], -1, 0
	s_add_u32 s8, s86, 0xe600000
	s_addc_u32 s9, s87, 0
	s_and_b64 s[10:11], s[4:5], s[0:1]
	s_andn2_b64 vcc, exec, s[10:11]
	s_cbranch_vccnz .LBB0_312
	s_mov_b64 s[0:1], exec

; #define PG8_STAGE(bufoff, gbase, voff) do { _Pragma("unroll") for (int _i = 0; _i < 2; ++_i) \
;         __builtin_amdgcn_global_load_lds((const unsigned*)((const char*)(gbase) + (voff)[_i]), (PG8_LAS unsigned*)(lds + (bufoff) + ldsw + _i * 8192), 16, 0, 0); } while (0)
; #define PG8_LDA(dst, b, h) do { _Pragma("unroll") for (int m = 0; m < 4; ++m) _Pragma("unroll") for (int k = 0; k < 2; ++k) dst[m][k] = *(const PG8_LAS bf16x8*)(lds + PG8_SA(b, h) + aoff + m * 2048 + k * 1024); } while (0)
; #define PG8_LDB(dst, b, h) do { _Pragma("unroll") for (int n = 0; n < 2; ++n) _Pragma("unroll") for (int k = 0; k < 2; ++k) dst[n][k] = *(const PG8_LAS bf16x8*)(lds + PG8_SB(b, h) + boff + n * 2048 + k * 1024); } while (0)
; #define PG8_MMA(ai, bj, At, Bt) do { __builtin_amdgcn_s_setprio(1); _Pragma("unroll") for (int m = 0; m < 4; ++m) _Pragma("unroll") for (int n = 0; n < 2; ++n) _Pragma("unroll") for (int k = 0; k < 2; ++k) \
;         acc[ai][bj][m][n] = __builtin_amdgcn_mfma_f32_16x16x32_bf16(Bt[n][k], At[m][k], acc[ai][bj][m][n], 0, 0, 0); __builtin_amdgcn_s_setprio(0); } while (0)
; #define PG8_WAIT_V(n) asm volatile("s_waitcnt vmcnt(" #n ")" ::: "memory")
; #define PG8_WAIT_L(n) asm volatile("s_waitcnt lgkmcnt(" #n ")" ::: "memory")
; #define PG8_BAR __builtin_amdgcn_s_barrier()
; #define PG8_SCHED __builtin_amdgcn_sched_barrier(0)
; template <class Epi, class Sched, bool ALIGN_EPI = false, bool SP2 = false>
; __device__ __forceinline__ void gemm_phase(PG8_LAS unsigned char* lds, const Gemm g, const Sched& S, const Epi& E) {
;     ...
;             PG8_LDB(B0, 0, 0); PG8_LDB(B1, 0, 1); PG8_SCHED; PG8_LDA(At, 0, 0); PG8_STAGE(PG8_SA(1, 1), a1 + hstep, voffA);
;             PG8_WAIT_V(8); PG8_WAIT_L(0); PG8_BAR; PG8_MMA(0, 0, At, B0); PG8_MMA(0, 1, At, B1); PG8_BAR; PG8_SCHED;
;             PG8_LDA(At, 0, 1); PG8_STAGE(PG8_SB(0, 0), b2, voffB); PG8_STAGE(PG8_SB(0, 1), b2 + hstep, voffB); PG8_STAGE(PG8_SA(0, 0), a2, voffA);
;             PG8_WAIT_V(8); PG8_WAIT_L(0); PG8_BAR; PG8_MMA(1, 0, At, B0); PG8_MMA(1, 1, At, B1); PG8_BAR; PG8_SCHED;
.LBB0_289:
	ds_read_b128 v[144:147], v168
	ds_read_b128 v[148:151], v168 offset:1024
	ds_read_b128 v[152:155], v168 offset:2048
	ds_read_b128 v[156:159], v168 offset:3072
	ds_read_b128 v[162:165], v169
	ds_read_b128 v[172:175], v169 offset:1024
	ds_read_b128 v[176:179], v169 offset:2048
	ds_read_b128 v[180:183], v169 offset:3072
	s_add_u32 s34, s22, 0xfff50080
	s_addc_u32 s35, s23, -1
	s_cmp_eq_u32 s70, 40
	s_cselect_b32 s37, s1, s35
	s_cselect_b32 s36, s0, s34
	s_cselect_b32 s35, s21, s67
	s_cselect_b32 s34, s20, s66
	v_lshl_add_u64 v[216:217], s[22:23], 0, v[136:137]
	s_add_i32 m0, s38, 0xc000
	ds_read_b128 v[184:187], v170
	ds_read_b128 v[188:191], v170 offset:1024
	ds_read_b128 v[192:195], v170 offset:2048
	ds_read_b128 v[196:199], v170 offset:3072
	ds_read_b128 v[200:203], v170 offset:4096
	ds_read_b128 v[204:207], v170 offset:5120
	ds_read_b128 v[208:211], v170 offset:6144
	ds_read_b128 v[212:215], v170 offset:7168
	global_load_lds_dwordx4 v[216:217], off
	v_lshl_add_u64 v[216:217], s[22:23], 0, v[138:139]
	s_add_i32 m0, s38, 0xe000
	s_nop 0
	global_load_lds_dwordx4 v[216:217], off
	s_waitcnt vmcnt(8)
	s_waitcnt lgkmcnt(0)
	s_barrier
	s_setprio 1
	s_waitcnt lgkmcnt(0)
	v_mfma_f32_16x16x32_bf16 v[124:127], v[144:147], v[184:187], v[124:127]
	v_mfma_f32_16x16x32_bf16 v[120:123], v[152:155], v[184:187], v[120:123]
	v_mfma_f32_16x16x32_bf16 v[108:111], v[144:147], v[192:195], v[108:111]
	v_mfma_f32_16x16x32_bf16 v[104:107], v[152:155], v[192:195], v[104:107]
	v_mfma_f32_16x16x32_bf16 v[92:95], v[144:147], v[200:203], v[92:95]
	v_mfma_f32_16x16x32_bf16 v[88:91], v[152:155], v[200:203], v[88:91]
	v_mfma_f32_16x16x32_bf16 v[76:79], v[144:147], v[208:211], v[76:79]
	v_mfma_f32_16x16x32_bf16 v[72:75], v[152:155], v[208:211], v[72:75]
	v_mfma_f32_16x16x32_bf16 v[124:127], v[148:151], v[188:191], v[124:127]
	v_mfma_f32_16x16x32_bf16 v[120:123], v[156:159], v[188:191], v[120:123]
	v_mfma_f32_16x16x32_bf16 v[108:111], v[148:151], v[196:199], v[108:111]
	v_mfma_f32_16x16x32_bf16 v[104:107], v[156:159], v[196:199], v[104:107]
	v_mfma_f32_16x16x32_bf16 v[92:95], v[148:151], v[204:207], v[92:95]
	v_mfma_f32_16x16x32_bf16 v[88:91], v[156:159], v[204:207], v[88:91]
	v_mfma_f32_16x16x32_bf16 v[76:79], v[148:151], v[212:215], v[76:79]
	v_mfma_f32_16x16x32_bf16 v[72:75], v[156:159], v[212:215], v[72:75]
	s_setprio 0
	s_setprio 1
	v_mfma_f32_16x16x32_bf16 v[116:119], v[162:165], v[184:187], v[116:119]
	v_mfma_f32_16x16x32_bf16 v[112:115], v[176:179], v[184:187], v[112:115]
	v_mfma_f32_16x16x32_bf16 v[100:103], v[162:165], v[192:195], v[100:103]
	v_mfma_f32_16x16x32_bf16 v[96:99], v[176:179], v[192:195], v[96:99]
	v_mfma_f32_16x16x32_bf16 v[84:87], v[162:165], v[200:203], v[84:87]
	v_mfma_f32_16x16x32_bf16 v[80:83], v[176:179], v[200:203], v[80:83]
	v_mfma_f32_16x16x32_bf16 v[68:71], v[162:165], v[208:211], v[68:71]
	v_mfma_f32_16x16x32_bf16 v[64:67], v[176:179], v[208:211], v[64:67]
	v_mfma_f32_16x16x32_bf16 v[116:119], v[172:175], v[188:191], v[116:119]
	v_mfma_f32_16x16x32_bf16 v[112:115], v[180:183], v[188:191], v[112:115]
	v_mfma_f32_16x16x32_bf16 v[100:103], v[172:175], v[196:199], v[100:103]
	v_mfma_f32_16x16x32_bf16 v[96:99], v[180:183], v[196:199], v[96:99]
	v_mfma_f32_16x16x32_bf16 v[84:87], v[172:175], v[204:207], v[84:87]
	v_mfma_f32_16x16x32_bf16 v[80:83], v[180:183], v[204:207], v[80:83]
	v_mfma_f32_16x16x32_bf16 v[68:71], v[172:175], v[212:215], v[68:71]
	v_mfma_f32_16x16x32_bf16 v[64:67], v[180:183], v[212:215], v[64:67]
	s_setprio 0
	s_barrier
	s_add_i32 s71, s58, s3
	v_lshl_add_u64 v[216:217], s[34:35], 0, v[130:131]
	s_mov_b32 m0, s71
	ds_read_b128 v[184:187], v170 offset:16384
	ds_read_b128 v[188:191], v170 offset:17408
	ds_read_b128 v[192:195], v170 offset:18432
	ds_read_b128 v[196:199], v170 offset:19456
	ds_read_b128 v[200:203], v170 offset:20480
	ds_read_b128 v[204:207], v170 offset:21504
	ds_read_b128 v[208:211], v170 offset:22528
	ds_read_b128 v[212:215], v170 offset:23552
	global_load_lds_dwordx4 v[216:217], off
	s_add_i32 m0, s71, 0x2000
	s_add_u32 s72, s34, 0xb0000
	v_lshl_add_u64 v[218:219], s[34:35], 0, v[134:135]
	s_addc_u32 s73, s35, 0
	s_add_i32 s71, s59, s3
	global_load_lds_dwordx4 v[218:219], off
	v_lshl_add_u64 v[220:221], s[72:73], 0, v[130:131]
	s_mov_b32 m0, s71
	v_lshl_add_u64 v[222:223], s[36:37], 0, v[132:133]
	global_load_lds_dwordx4 v[220:221], off
	v_lshl_add_u64 v[220:221], s[72:73], 0, v[134:135]
	s_add_i32 m0, s71, 0x2000
	s_nop 0
	global_load_lds_dwordx4 v[220:221], off
	v_lshl_add_u64 v[220:221], s[36:37], 0, v[128:129]
	s_mov_b32 m0, s38
	s_nop 0
	global_load_lds_dwordx4 v[220:221], off
	s_mov_b32 m0, s39
	s_nop 0
	global_load_lds_dwordx4 v[222:223], off
	s_waitcnt vmcnt(8)
	s_waitcnt lgkmcnt(0)
	s_barrier
; #define PG8_STAGE(bufoff, gbase, voff) do { _Pragma("unroll") for (int _i = 0; _i < 2; ++_i) \
;         __builtin_amdgcn_global_load_lds((const unsigned*)((const char*)(gbase) + (voff)[_i]), (PG8_LAS unsigned*)(lds + (bufoff) + ldsw + _i * 8192), 16, 0, 0); } while (0)
; #define PG8_LDA(dst, b, h) do { _Pragma("unroll") for (int m = 0; m < 4; ++m) _Pragma("unroll") for (int k = 0; k < 2; ++k) dst[m][k] = *(const PG8_LAS bf16x8*)(lds + PG8_SA(b, h) + aoff + m * 2048 + k * 1024); } while (0)
; #define PG8_LDB(dst, b, h) do { _Pragma("unroll") for (int n = 0; n < 2; ++n) _Pragma("unroll") for (int k = 0; k < 2; ++k) dst[n][k] = *(const PG8_LAS bf16x8*)(lds + PG8_SB(b, h) + boff + n * 2048 + k * 1024); } while (0)
; #define PG8_MMA(ai, bj, At, Bt) do { __builtin_amdgcn_s_setprio(1); _Pragma("unroll") for (int m = 0; m < 4; ++m) _Pragma("unroll") for (int n = 0; n < 2; ++n) _Pragma("unroll") for (int k = 0; k < 2; ++k) \
;         acc[ai][bj][m][n] = __builtin_amdgcn_mfma_f32_16x16x32_bf16(Bt[n][k], At[m][k], acc[ai][bj][m][n], 0, 0, 0); __builtin_amdgcn_s_setprio(0); } while (0)
; #define PG8_WAIT_V(n) asm volatile("s_waitcnt vmcnt(" #n ")" ::: "memory")
; #define PG8_WAIT_L(n) asm volatile("s_waitcnt lgkmcnt(" #n ")" ::: "memory")
; #define PG8_BAR __builtin_amdgcn_s_barrier()
; #define PG8_SCHED __builtin_amdgcn_sched_barrier(0)
; template <class Epi, class Sched, bool ALIGN_EPI = false, bool SP2 = false>
; __device__ __forceinline__ void gemm_phase(PG8_LAS unsigned char* lds, const Gemm g, const Sched& S, const Epi& E) {
;     ...
;             PG8_WAIT_V(8); PG8_WAIT_L(0); PG8_BAR; PG8_MMA(1, 0, At, B0); PG8_MMA(1, 1, At, B1); PG8_BAR; PG8_SCHED;
;             PG8_LDB(B0, 1, 0); PG8_LDB(B1, 1, 1); PG8_SCHED; PG8_LDA(At, 1, 0); PG8_STAGE(PG8_SA(0, 1), a2 + hstep, voffA);
;             PG8_WAIT_V(8); PG8_WAIT_L(0); PG8_BAR; PG8_MMA(0, 0, At, B0); PG8_MMA(0, 1, At, B1); PG8_BAR; PG8_SCHED;
	s_setprio 1
	s_waitcnt lgkmcnt(0)
	v_mfma_f32_16x16x32_bf16 v[60:63], v[144:147], v[184:187], v[60:63]
	v_mfma_f32_16x16x32_bf16 v[56:59], v[152:155], v[184:187], v[56:59]
	v_mfma_f32_16x16x32_bf16 v[44:47], v[144:147], v[192:195], v[44:47]
	v_mfma_f32_16x16x32_bf16 v[40:43], v[152:155], v[192:195], v[40:43]
	v_mfma_f32_16x16x32_bf16 v[28:31], v[144:147], v[200:203], v[28:31]
	v_mfma_f32_16x16x32_bf16 v[24:27], v[152:155], v[200:203], v[24:27]
	v_mfma_f32_16x16x32_bf16 v[12:15], v[144:147], v[208:211], v[12:15]
	v_mfma_f32_16x16x32_bf16 v[8:11], v[152:155], v[208:211], v[8:11]
	v_mfma_f32_16x16x32_bf16 v[60:63], v[148:151], v[188:191], v[60:63]
	v_mfma_f32_16x16x32_bf16 v[56:59], v[156:159], v[188:191], v[56:59]
	v_mfma_f32_16x16x32_bf16 v[44:47], v[148:151], v[196:199], v[44:47]
	v_mfma_f32_16x16x32_bf16 v[40:43], v[156:159], v[196:199], v[40:43]
	v_mfma_f32_16x16x32_bf16 v[28:31], v[148:151], v[204:207], v[28:31]
	v_mfma_f32_16x16x32_bf16 v[24:27], v[156:159], v[204:207], v[24:27]
	v_mfma_f32_16x16x32_bf16 v[12:15], v[148:151], v[212:215], v[12:15]
	v_mfma_f32_16x16x32_bf16 v[8:11], v[156:159], v[212:215], v[8:11]
	s_setprio 0
	s_setprio 1
	v_mfma_f32_16x16x32_bf16 v[52:55], v[162:165], v[184:187], v[52:55]
	v_mfma_f32_16x16x32_bf16 v[48:51], v[176:179], v[184:187], v[48:51]
	v_mfma_f32_16x16x32_bf16 v[36:39], v[162:165], v[192:195], v[36:39]
	v_mfma_f32_16x16x32_bf16 v[32:35], v[176:179], v[192:195], v[32:35]
	v_mfma_f32_16x16x32_bf16 v[20:23], v[162:165], v[200:203], v[20:23]
	v_mfma_f32_16x16x32_bf16 v[16:19], v[176:179], v[200:203], v[16:19]
	v_mfma_f32_16x16x32_bf16 v[4:7], v[162:165], v[208:211], v[4:7]
	v_mfma_f32_16x16x32_bf16 v[0:3], v[176:179], v[208:211], v[0:3]
	v_mfma_f32_16x16x32_bf16 v[52:55], v[172:175], v[188:191], v[52:55]
	v_mfma_f32_16x16x32_bf16 v[48:51], v[180:183], v[188:191], v[48:51]
	v_mfma_f32_16x16x32_bf16 v[36:39], v[172:175], v[196:199], v[36:39]
	v_mfma_f32_16x16x32_bf16 v[32:35], v[180:183], v[196:199], v[32:35]
	v_mfma_f32_16x16x32_bf16 v[20:23], v[172:175], v[204:207], v[20:23]
	v_mfma_f32_16x16x32_bf16 v[16:19], v[180:183], v[204:207], v[16:19]
	v_mfma_f32_16x16x32_bf16 v[4:7], v[172:175], v[212:215], v[4:7]
	v_mfma_f32_16x16x32_bf16 v[0:3], v[180:183], v[212:215], v[0:3]
	s_setprio 0
	s_barrier
	s_add_i32 s71, 0, 0x18000
	s_add_i32 s72, 0, 0x1c000
	v_add_u32_e32 v156, s71, v166
	v_add_u32_e32 v180, s72, v166
	ds_read_b128 v[144:147], v156
	ds_read_b128 v[148:151], v156 offset:1024
	ds_read_b128 v[152:155], v156 offset:2048
	ds_read_b128 v[156:159], v156 offset:3072
	ds_read_b128 v[162:165], v180
	ds_read_b128 v[172:175], v180 offset:1024
	ds_read_b128 v[176:179], v180 offset:2048
	ds_read_b128 v[180:183], v180 offset:3072
	s_add_u32 s36, s36, 0xb0000
	s_addc_u32 s37, s37, 0
	s_mov_b32 m0, s40
	v_lshl_add_u64 v[224:225], s[36:37], 0, v[128:129]
	ds_read_b128 v[184:187], v170 offset:32768
	ds_read_b128 v[188:191], v170 offset:33792
	ds_read_b128 v[192:195], v170 offset:34816
	ds_read_b128 v[196:199], v170 offset:35840
	ds_read_b128 v[200:203], v170 offset:36864
	ds_read_b128 v[204:207], v170 offset:37888
	ds_read_b128 v[208:211], v170 offset:38912
	ds_read_b128 v[212:215], v170 offset:39936
	global_load_lds_dwordx4 v[224:225], off
	v_lshl_add_u64 v[224:225], s[36:37], 0, v[132:133]
	s_mov_b32 m0, s41
	s_nop 0
	global_load_lds_dwordx4 v[224:225], off
	s_waitcnt vmcnt(8)
	s_waitcnt lgkmcnt(0)
	s_barrier
	s_setprio 1
	s_waitcnt lgkmcnt(0)
	v_mfma_f32_16x16x32_bf16 v[124:127], v[144:147], v[184:187], v[124:127]
	v_mfma_f32_16x16x32_bf16 v[120:123], v[152:155], v[184:187], v[120:123]
	v_mfma_f32_16x16x32_bf16 v[108:111], v[144:147], v[192:195], v[108:111]
	v_mfma_f32_16x16x32_bf16 v[104:107], v[152:155], v[192:195], v[104:107]
	v_mfma_f32_16x16x32_bf16 v[92:95], v[144:147], v[200:203], v[92:95]
	v_mfma_f32_16x16x32_bf16 v[88:91], v[152:155], v[200:203], v[88:91]
	v_mfma_f32_16x16x32_bf16 v[76:79], v[144:147], v[208:211], v[76:79]
	v_mfma_f32_16x16x32_bf16 v[72:75], v[152:155], v[208:211], v[72:75]
	v_mfma_f32_16x16x32_bf16 v[124:127], v[148:151], v[188:191], v[124:127]
	v_mfma_f32_16x16x32_bf16 v[120:123], v[156:159], v[188:191], v[120:123]
	v_mfma_f32_16x16x32_bf16 v[108:111], v[148:151], v[196:199], v[108:111]
	v_mfma_f32_16x16x32_bf16 v[104:107], v[156:159], v[196:199], v[104:107]
	v_mfma_f32_16x16x32_bf16 v[92:95], v[148:151], v[204:207], v[92:95]
	v_mfma_f32_16x16x32_bf16 v[88:91], v[156:159], v[204:207], v[88:91]
	v_mfma_f32_16x16x32_bf16 v[76:79], v[148:151], v[212:215], v[76:79]
	v_mfma_f32_16x16x32_bf16 v[72:75], v[156:159], v[212:215], v[72:75]
	s_setprio 0
	s_setprio 1
	v_mfma_f32_16x16x32_bf16 v[116:119], v[162:165], v[184:187], v[116:119]
	v_mfma_f32_16x16x32_bf16 v[112:115], v[176:179], v[184:187], v[112:115]
	v_mfma_f32_16x16x32_bf16 v[100:103], v[162:165], v[192:195], v[100:103]
	v_mfma_f32_16x16x32_bf16 v[96:99], v[176:179], v[192:195], v[96:99]
	v_mfma_f32_16x16x32_bf16 v[84:87], v[162:165], v[200:203], v[84:87]
	v_mfma_f32_16x16x32_bf16 v[80:83], v[176:179], v[200:203], v[80:83]
	v_mfma_f32_16x16x32_bf16 v[68:71], v[162:165], v[208:211], v[68:71]
	v_mfma_f32_16x16x32_bf16 v[64:67], v[176:179], v[208:211], v[64:67]
	v_mfma_f32_16x16x32_bf16 v[116:119], v[172:175], v[188:191], v[116:119]
	v_mfma_f32_16x16x32_bf16 v[112:115], v[180:183], v[188:191], v[112:115]
	v_mfma_f32_16x16x32_bf16 v[100:103], v[172:175], v[196:199], v[100:103]
	v_mfma_f32_16x16x32_bf16 v[96:99], v[180:183], v[196:199], v[96:99]
	v_mfma_f32_16x16x32_bf16 v[84:87], v[172:175], v[204:207], v[84:87]
	v_mfma_f32_16x16x32_bf16 v[80:83], v[180:183], v[204:207], v[80:83]
	v_mfma_f32_16x16x32_bf16 v[68:71], v[172:175], v[212:215], v[68:71]
	v_mfma_f32_16x16x32_bf16 v[64:67], v[180:183], v[212:215], v[64:67]
	s_setprio 0
	s_barrier
; #define PG8_STAGE(bufoff, gbase, voff) do { _Pragma("unroll") for (int _i = 0; _i < 2; ++_i) \
;         __builtin_amdgcn_global_load_lds((const unsigned*)((const char*)(gbase) + (voff)[_i]), (PG8_LAS unsigned*)(lds + (bufoff) + ldsw + _i * 8192), 16, 0, 0); } while (0)
; #define PG8_LDA(dst, b, h) do { _Pragma("unroll") for (int m = 0; m < 4; ++m) _Pragma("unroll") for (int k = 0; k < 2; ++k) dst[m][k] = *(const PG8_LAS bf16x8*)(lds + PG8_SA(b, h) + aoff + m * 2048 + k * 1024); } while (0)
; #define PG8_MMA(ai, bj, At, Bt) do { __builtin_amdgcn_s_setprio(1); _Pragma("unroll") for (int m = 0; m < 4; ++m) _Pragma("unroll") for (int n = 0; n < 2; ++n) _Pragma("unroll") for (int k = 0; k < 2; ++k) \
;         acc[ai][bj][m][n] = __builtin_amdgcn_mfma_f32_16x16x32_bf16(Bt[n][k], At[m][k], acc[ai][bj][m][n], 0, 0, 0); __builtin_amdgcn_s_setprio(0); } while (0)
; #define PG8_WAIT_V(n) asm volatile("s_waitcnt vmcnt(" #n ")" ::: "memory")
; #define PG8_WAIT_L(n) asm volatile("s_waitcnt lgkmcnt(" #n ")" ::: "memory")
; #define PG8_BAR __builtin_amdgcn_s_barrier()
; #define PG8_SCHED __builtin_amdgcn_sched_barrier(0)
; template <class Epi, class Sched, bool ALIGN_EPI = false, bool SP2 = false>
; __device__ __forceinline__ void gemm_phase(PG8_LAS unsigned char* lds, const Gemm g, const Sched& S, const Epi& E) {
;     ...
;             PG8_WAIT_V(8); PG8_WAIT_L(0); PG8_BAR; PG8_MMA(0, 0, At, B0); PG8_MMA(0, 1, At, B1); PG8_BAR; PG8_SCHED;
;             PG8_LDA(At, 1, 1); PG8_STAGE(PG8_SB(1, 0), b3, voffB); PG8_STAGE(PG8_SB(1, 1), b3 + hstep, voffB); PG8_STAGE(PG8_SA(1, 0), a3, voffA);
;             PG8_WAIT_V(8); PG8_WAIT_L(0); PG8_BAR; PG8_MMA(1, 0, At, B0); PG8_MMA(1, 1, At, B1); PG8_BAR; PG8_SCHED;
; __global__ void __launch_bounds__(512, 2) hybrid_fwd(Args args) {
;     ...
;         for (int idx = blk * 512 + tid; idx < 2 * NBIAS; idx += G * 512) { const int bb = idx / NBIAS, col = idx - bb * NBIAS; float sacc = 0.f;
; #pragma unroll
;             for (int kb = 0; kb < 16; ++kb) sacc += BIASP[((size_t)bb * 16 + kb) * NBIAS + col];
;             BIAS[idx] = sacc; }
	s_add_i32 s36, s71, s3
	v_lshl_add_u64 v[216:217], v[216:217], 0, s[16:17]
	s_mov_b32 m0, s36
	ds_read_b128 v[184:187], v170 offset:49152
	ds_read_b128 v[188:191], v170 offset:50176
	ds_read_b128 v[192:195], v170 offset:51200
	ds_read_b128 v[196:199], v170 offset:52224
	ds_read_b128 v[200:203], v170 offset:53248
	ds_read_b128 v[204:207], v170 offset:54272
	ds_read_b128 v[208:211], v170 offset:55296
	ds_read_b128 v[212:215], v170 offset:56320
	global_load_lds_dwordx4 v[216:217], off
	s_add_i32 m0, s36, 0x2000
	s_add_u32 s34, s34, 0xb0080
	v_lshl_add_u64 v[216:217], v[218:219], 0, s[16:17]
	s_addc_u32 s35, s35, 0
	s_add_i32 s36, s72, s3
	global_load_lds_dwordx4 v[216:217], off
	v_lshl_add_u64 v[216:217], s[34:35], 0, v[130:131]
	s_mov_b32 m0, s36
	s_nop 0
	global_load_lds_dwordx4 v[216:217], off
	v_lshl_add_u64 v[216:217], s[34:35], 0, v[134:135]
	s_add_i32 m0, s36, 0x2000
	s_nop 0
	global_load_lds_dwordx4 v[216:217], off
	v_lshl_add_u64 v[216:217], v[220:221], 0, s[16:17]
	s_mov_b32 m0, s53
	s_nop 0
	global_load_lds_dwordx4 v[216:217], off
	v_lshl_add_u64 v[216:217], v[222:223], 0, s[16:17]
	s_mov_b32 m0, s54
	s_nop 0
	global_load_lds_dwordx4 v[216:217], off
	s_waitcnt vmcnt(8)
	s_waitcnt lgkmcnt(0)
	s_barrier
	s_setprio 1
	s_waitcnt lgkmcnt(0)
	v_mfma_f32_16x16x32_bf16 v[60:63], v[144:147], v[184:187], v[60:63]
	v_mfma_f32_16x16x32_bf16 v[56:59], v[152:155], v[184:187], v[56:59]
	v_mfma_f32_16x16x32_bf16 v[44:47], v[144:147], v[192:195], v[44:47]
	v_mfma_f32_16x16x32_bf16 v[40:43], v[152:155], v[192:195], v[40:43]
	v_mfma_f32_16x16x32_bf16 v[28:31], v[144:147], v[200:203], v[28:31]
	v_mfma_f32_16x16x32_bf16 v[24:27], v[152:155], v[200:203], v[24:27]
	v_mfma_f32_16x16x32_bf16 v[12:15], v[144:147], v[208:211], v[12:15]
	v_mfma_f32_16x16x32_bf16 v[8:11], v[152:155], v[208:211], v[8:11]
	v_mfma_f32_16x16x32_bf16 v[60:63], v[148:151], v[188:191], v[60:63]
	v_mfma_f32_16x16x32_bf16 v[56:59], v[156:159], v[188:191], v[56:59]
	v_mfma_f32_16x16x32_bf16 v[44:47], v[148:151], v[196:199], v[44:47]
	v_mfma_f32_16x16x32_bf16 v[40:43], v[156:159], v[196:199], v[40:43]
	v_mfma_f32_16x16x32_bf16 v[28:31], v[148:151], v[204:207], v[28:31]
	v_mfma_f32_16x16x32_bf16 v[24:27], v[156:159], v[204:207], v[24:27]
	v_mfma_f32_16x16x32_bf16 v[12:15], v[148:151], v[212:215], v[12:15]
	v_mfma_f32_16x16x32_bf16 v[8:11], v[156:159], v[212:215], v[8:11]
	s_setprio 0
	s_setprio 1
	v_mfma_f32_16x16x32_bf16 v[52:55], v[162:165], v[184:187], v[52:55]
	v_mfma_f32_16x16x32_bf16 v[48:51], v[176:179], v[184:187], v[48:51]
	v_mfma_f32_16x16x32_bf16 v[36:39], v[162:165], v[192:195], v[36:39]
	v_mfma_f32_16x16x32_bf16 v[32:35], v[176:179], v[192:195], v[32:35]
	v_mfma_f32_16x16x32_bf16 v[20:23], v[162:165], v[200:203], v[20:23]
	v_mfma_f32_16x16x32_bf16 v[16:19], v[176:179], v[200:203], v[16:19]
	v_mfma_f32_16x16x32_bf16 v[4:7], v[162:165], v[208:211], v[4:7]
	v_mfma_f32_16x16x32_bf16 v[0:3], v[176:179], v[208:211], v[0:3]
	v_mfma_f32_16x16x32_bf16 v[52:55], v[172:175], v[188:191], v[52:55]
	v_mfma_f32_16x16x32_bf16 v[48:51], v[180:183], v[188:191], v[48:51]
	v_mfma_f32_16x16x32_bf16 v[36:39], v[172:175], v[196:199], v[36:39]
	v_mfma_f32_16x16x32_bf16 v[32:35], v[180:183], v[196:199], v[32:35]
	v_mfma_f32_16x16x32_bf16 v[20:23], v[172:175], v[204:207], v[20:23]
	v_mfma_f32_16x16x32_bf16 v[16:19], v[180:183], v[204:207], v[16:19]
	v_mfma_f32_16x16x32_bf16 v[4:7], v[172:175], v[212:215], v[4:7]
	v_mfma_f32_16x16x32_bf16 v[0:3], v[180:183], v[212:215], v[0:3]
	s_setprio 0
	s_barrier
	s_add_i32 s70, s70, 2
	s_add_u32 s22, s22, 0x100
	s_addc_u32 s23, s23, 0
	s_add_u32 s66, s66, 0x100
	s_addc_u32 s67, s67, 0
	s_cmp_gt_u32 s70, 41
	s_cbranch_scc0 .LBB0_289
	s_cmp_lt_u32 s2, 38
	s_cbranch_scc0 .Lp3_bias_noload
	s_cmp_ge_u32 s2, 19
	s_cselect_b32 s99, 0x98000, 0
	s_cselect_b32 s100, 19, 0
	s_sub_i32 s100, s2, s100
	s_lshl_b32 s100, s100, 11
	s_add_u32 s100, s100, s99
	s_add_u32 s100, s100, 0xe800000
	s_add_u32 s100, s86, s100
	s_addc_u32 s101, s87, 0
	v_lshlrev_b32_e32 v227, 2, v226
	global_load_dword v228, v227, s[100:101]
	s_add_u32 s100, s100, 0x9800
	s_addc_u32 s101, s101, 0
	global_load_dword v229, v227, s[100:101]
	s_add_u32 s100, s100, 0x9800
	s_addc_u32 s101, s101, 0
	global_load_dword v230, v227, s[100:101]
	s_add_u32 s100, s100, 0x9800
	s_addc_u32 s101, s101, 0
	global_load_dword v231, v227, s[100:101]
	s_add_u32 s100, s100, 0x9800
	s_addc_u32 s101, s101, 0
	global_load_dword v232, v227, s[100:101]
	s_add_u32 s100, s100, 0x9800
	s_addc_u32 s101, s101, 0
	global_load_dword v233, v227, s[100:101]
	s_add_u32 s100, s100, 0x9800
	s_addc_u32 s101, s101, 0
	global_load_dword v234, v227, s[100:101]
	s_add_u32 s100, s100, 0x9800
	s_addc_u32 s101, s101, 0
	global_load_dword v235, v227, s[100:101]
	s_add_u32 s100, s100, 0x9800
	s_addc_u32 s101, s101, 0
	global_load_dword v236, v227, s[100:101]
	s_add_u32 s100, s100, 0x9800
	s_addc_u32 s101, s101, 0
	global_load_dword v237, v227, s[100:101]
	s_add_u32 s100, s100, 0x9800
	s_addc_u32 s101, s101, 0
	global_load_dword v238, v227, s[100:101]
	s_add_u32 s100, s100, 0x9800
	s_addc_u32 s101, s101, 0
	global_load_dword v239, v227, s[100:101]
	s_add_u32 s100, s100, 0x9800
	s_addc_u32 s101, s101, 0
	global_load_dword v240, v227, s[100:101]
	s_add_u32 s100, s100, 0x9800
	s_addc_u32 s101, s101, 0
	global_load_dword v241, v227, s[100:101]
	s_add_u32 s100, s100, 0x9800
	s_addc_u32 s101, s101, 0
	global_load_dword v242, v227, s[100:101]
	s_add_u32 s100, s100, 0x9800
	s_addc_u32 s101, s101, 0
	global_load_dword v243, v227, s[100:101]
.Lp3_bias_noload:
	s_and_b64 vcc, exec, s[18:19]
	s_cbranch_vccz .LBB0_292
	s_barrier

; __global__ void __launch_bounds__(512, 2) hybrid_fwd(Args args) {
;     ...
;         for (int idx = blk * 512 + tid; idx < 2 * NBIAS; idx += G * 512) { const int bb = idx / NBIAS, col = idx - bb * NBIAS; float sacc = 0.f;
; #pragma unroll
;             for (int kb = 0; kb < 16; ++kb) sacc += BIASP[((size_t)bb * 16 + kb) * NBIAS + col];
;             BIAS[idx] = sacc; }
.LBB0_308:
	s_or_b64 exec, exec, s[34:35]
	s_cmp_lt_u32 s2, 38
	s_cbranch_scc0 .Lp3_bias_nosum
	s_waitcnt vmcnt(0)
	v_add_f32_e32 v244, 0, v228
	v_add_f32_e32 v244, v244, v229
	v_add_f32_e32 v244, v244, v230
	v_add_f32_e32 v244, v244, v231
	v_add_f32_e32 v244, v244, v232
	v_add_f32_e32 v244, v244, v233
	v_add_f32_e32 v244, v244, v234
	v_add_f32_e32 v244, v244, v235
	v_add_f32_e32 v244, v244, v236
	v_add_f32_e32 v244, v244, v237
	v_add_f32_e32 v244, v244, v238
	v_add_f32_e32 v244, v244, v239
	v_add_f32_e32 v244, v244, v240
	v_add_f32_e32 v244, v244, v241
	v_add_f32_e32 v244, v244, v242
	v_add_f32_e32 v244, v244, v243
	v_lshl_add_u32 v246, s2, 9, v226
	v_mov_b32_e32 v247, 0
	s_mov_b64 s[100:101], 0xea00000
	v_lshl_add_u64 v[246:247], v[246:247], 2, s[86:87]
	v_lshl_add_u64 v[246:247], v[246:247], 0, s[100:101]
	global_store_dword v[246:247], v244, off
.Lp3_bias_nosum:
	s_and_b64 vcc, exec, s[6:7]
	s_mov_b64 s[6:7], -1
	s_cbranch_vccnz .LBB0_277
	s_andn2_b64 vcc, exec, s[14:15]
	s_cbranch_vccnz .LBB0_276
	s_barrier
	s_branch .LBB0_276
